# G6 ring K-loop: next K-step LDS fragment reads interleaved one per MFMA gap (register double buffer)
# speedup vs baseline: 1.0093x; 1.0093x over previous
.LBB0_228:
	s_or_b64 exec, exec, s[6:7]
	s_add_i32 s6, s13, 0
	v_add_u32_e32 v131, s6, v182
	v_add_u32_e32 v130, v246, v183
	v_add_u32_e32 v133, v131, v184
	v_add_u32_e32 v230, v130, v184
	ds_read_b128 v[190:193], v133
	ds_read_b128 v[194:197], v133 offset:4096
	ds_read_b128 v[198:201], v133 offset:8192
	ds_read_b128 v[206:209], v230 offset:32768
	ds_read_b128 v[210:213], v230 offset:36864
	v_add_u32_e32 v133, v131, v181
	v_add_u32_e32 v230, v130, v181
	s_setprio 1
	s_waitcnt lgkmcnt(0)
	v_mfma_f32_32x32x16_bf16 v[112:127], v[190:193], v[206:209], v[112:127]
	ds_read_b128 v[214:217], v133
	v_mfma_f32_32x32x16_bf16 v[96:111], v[190:193], v[210:213], v[96:111]
	ds_read_b128 v[218:221], v133 offset:4096
	v_mfma_f32_32x32x16_bf16 v[80:95], v[194:197], v[206:209], v[80:95]
	ds_read_b128 v[234:237], v133 offset:8192
	v_mfma_f32_32x32x16_bf16 v[64:79], v[194:197], v[210:213], v[64:79]
	ds_read_b128 v[238:241], v230 offset:32768
	v_mfma_f32_32x32x16_bf16 v[48:63], v[198:201], v[206:209], v[48:63]
	ds_read_b128 v[242:245], v230 offset:36864
	v_mfma_f32_32x32x16_bf16 v[32:47], v[198:201], v[210:213], v[32:47]
	s_setprio 0
	v_add_u32_e32 v133, v131, v172
	v_add_u32_e32 v230, v130, v172
	s_setprio 1
	s_waitcnt lgkmcnt(0)
	v_mfma_f32_32x32x16_bf16 v[112:127], v[214:217], v[238:241], v[112:127]
	ds_read_b128 v[190:193], v133
	v_mfma_f32_32x32x16_bf16 v[96:111], v[214:217], v[242:245], v[96:111]
	ds_read_b128 v[194:197], v133 offset:4096
	v_mfma_f32_32x32x16_bf16 v[80:95], v[218:221], v[238:241], v[80:95]
	ds_read_b128 v[198:201], v133 offset:8192
	v_mfma_f32_32x32x16_bf16 v[64:79], v[218:221], v[242:245], v[64:79]
	ds_read_b128 v[206:209], v230 offset:32768
	v_mfma_f32_32x32x16_bf16 v[48:63], v[234:237], v[238:241], v[48:63]
	ds_read_b128 v[210:213], v230 offset:36864
	v_mfma_f32_32x32x16_bf16 v[32:47], v[234:237], v[242:245], v[32:47]
	s_setprio 0
	s_and_saveexec_b64 s[6:7], s[0:1]
	s_cbranch_execz .LBB0_230
	s_xor_b32 s14, s13, 0x22000
	v_add_u32_e32 v133, s14, v180
	v_lshl_add_u64 v[228:229], v[150:151], 0, s[4:5]
	v_readfirstlane_b32 s15, v133
	s_nop 0
	s_mov_b32 m0, s15
	s_nop 0
	global_load_lds_dwordx4 v[228:229], off
	v_add_u32_e32 v133, s14, v179
	v_lshl_add_u64 v[228:229], v[152:153], 0, s[4:5]
	v_readfirstlane_b32 s15, v133
	s_nop 0
	s_mov_b32 m0, s15
	s_nop 0
	global_load_lds_dwordx4 v[228:229], off
	v_add_u32_e32 v133, s14, v178
	v_lshl_add_u64 v[228:229], v[154:155], 0, s[4:5]
	v_readfirstlane_b32 s15, v133
	s_nop 0
	s_mov_b32 m0, s15
	s_nop 0
	global_load_lds_dwordx4 v[228:229], off
	v_add_u32_e32 v249, 0x8000, v248
	v_add_u32_e32 v133, v249, v180
	v_lshl_add_u64 v[228:229], v[158:159], 0, s[4:5]
	v_readfirstlane_b32 s15, v133
	s_nop 0
	s_mov_b32 m0, s15
	s_nop 0
	global_load_lds_dwordx4 v[228:229], off
	v_add_u32_e32 v133, v249, v179
	v_lshl_add_u64 v[228:229], v[160:161], 0, s[4:5]
	v_readfirstlane_b32 s15, v133
	s_nop 0
	s_mov_b32 m0, s15
	s_nop 0
	global_load_lds_dwordx4 v[228:229], off
	v_add_u32_e32 v133, v249, v178
	v_lshl_add_u64 v[228:229], v[162:163], 0, s[4:5]
	v_readfirstlane_b32 s15, v133
	s_nop 0
	s_mov_b32 m0, s15
	s_nop 0
	global_load_lds_dwordx4 v[228:229], off
	v_add_u32_e32 v133, v249, v177
	v_lshl_add_u64 v[228:229], v[164:165], 0, s[4:5]
	v_readfirstlane_b32 s15, v133
	s_nop 0
	s_mov_b32 m0, s15
	s_nop 0
	global_load_lds_dwordx4 v[228:229], off
.LBB0_230:
	s_or_b64 exec, exec, s[6:7]
	v_add_u32_e32 v133, v131, v171
	v_add_u32_e32 v230, v130, v171
	s_setprio 1
	s_waitcnt lgkmcnt(0)
	v_mfma_f32_32x32x16_bf16 v[112:127], v[190:193], v[206:209], v[112:127]
	ds_read_b128 v[214:217], v133
	v_mfma_f32_32x32x16_bf16 v[96:111], v[190:193], v[210:213], v[96:111]
	ds_read_b128 v[218:221], v133 offset:4096
	v_mfma_f32_32x32x16_bf16 v[80:95], v[194:197], v[206:209], v[80:95]
	ds_read_b128 v[234:237], v133 offset:8192
	v_mfma_f32_32x32x16_bf16 v[64:79], v[194:197], v[210:213], v[64:79]
	ds_read_b128 v[238:241], v230 offset:32768
	v_mfma_f32_32x32x16_bf16 v[48:63], v[198:201], v[206:209], v[48:63]
	ds_read_b128 v[242:245], v230 offset:36864
	v_mfma_f32_32x32x16_bf16 v[32:47], v[198:201], v[210:213], v[32:47]
	s_setprio 0
	s_setprio 1
	s_waitcnt lgkmcnt(0)
	v_mfma_f32_32x32x16_bf16 v[112:127], v[214:217], v[238:241], v[112:127]
	v_mfma_f32_32x32x16_bf16 v[96:111], v[214:217], v[242:245], v[96:111]
	v_mfma_f32_32x32x16_bf16 v[80:95], v[218:221], v[238:241], v[80:95]
	v_mfma_f32_32x32x16_bf16 v[64:79], v[218:221], v[242:245], v[64:79]
	v_mfma_f32_32x32x16_bf16 v[48:63], v[234:237], v[238:241], v[48:63]
	v_mfma_f32_32x32x16_bf16 v[32:47], v[234:237], v[242:245], v[32:47]
	s_setprio 0
	s_xor_b32 s6, s9, 1
	v_mov_b32_e32 v249, v246
	v_mov_b32_e32 v246, v247
	v_mov_b32_e32 v247, v248
	v_mov_b32_e32 v248, v249
	s_waitcnt vmcnt(4)
	s_add_u32 s4, s4, 0x80
	s_addc_u32 s5, s5, 0
	s_cmpk_lg_i32 s4, 0x1f80
	s_waitcnt vmcnt(4)
	s_barrier
	s_cbranch_scc1 .LBB0_226
	v_add_u32_e32 v147, s8, v128
	v_cmp_lt_i32_e64 s[0:1], 31, v147
	s_xor_b64 s[4:5], vcc, -1
	s_nor_b64 s[4:5], s[4:5], s[0:1]
	v_cndmask_b32_e64 v128, v147, v128, s[0:1]
	v_ashrrev_i32_e32 v130, 31, v128
	v_lshrrev_b32_e32 v130, 30, v130
	v_add_u32_e32 v130, v128, v130
	v_lshrrev_b32_e32 v131, 2, v130
	v_and_b32_e32 v130, 0xfffffc, v130
	v_sub_u32_e32 v130, v128, v130
	v_lshlrev_b32_e32 v128, 4, v132
	v_and_b32_e32 v128, 0x70, v128
	v_add_lshl_u32 v146, v131, v166, 8
	v_lshl_add_u64 v[136:137], s[38:39], 0, v[128:129]
	v_lshl_add_u64 v[134:135], s[40:41], 0, v[128:129]
	v_lshlrev_b32_e32 v148, 8, v130
	s_and_saveexec_b64 s[14:15], s[4:5]
	s_xor_b64 s[4:5], exec, s[14:15]
	s_cbranch_execz .LBB0_233
	s_lshl_b32 s7, s6, 16
	s_xor_b32 s13, s7, 0x10000
	v_add_u32_e32 v130, v146, v188
	s_add_i32 s13, s13, 0
	v_ashrrev_i32_e32 v131, 31, v130
	v_add_u32_e32 v132, v187, v146
	v_add_u32_e32 v128, s13, v180
	v_lshlrev_b64 v[130:131], 13, v[130:131]
	v_ashrrev_i32_e32 v133, 31, v132
	v_readfirstlane_b32 s14, v128
	v_add_u32_e32 v142, s13, v179
	v_lshl_add_u64 v[130:131], v[136:137], 0, v[130:131]
	v_lshlrev_b64 v[132:133], 13, v[132:133]
	s_mov_b32 m0, s14
	v_readfirstlane_b32 s14, v142
	v_lshl_add_u64 v[132:133], v[136:137], 0, v[132:133]
	v_add_u32_e32 v138, v186, v146
	global_load_lds_dwordx4 v[130:131], off
	s_mov_b32 m0, s14
	v_ashrrev_i32_e32 v139, 31, v138
	v_add_u32_e32 v140, v185, v146
	global_load_lds_dwordx4 v[132:133], off
	v_add_u32_e32 v132, s13, v178
	v_lshlrev_b64 v[138:139], 13, v[138:139]
	v_ashrrev_i32_e32 v141, 31, v140
	v_readfirstlane_b32 s14, v132
	v_add_u32_e32 v133, s13, v177
	v_add_u32_e32 v130, v148, v188
	v_lshl_add_u64 v[138:139], v[136:137], 0, v[138:139]
	v_lshlrev_b64 v[140:141], 13, v[140:141]
	s_mov_b32 m0, s14
	v_readfirstlane_b32 s13, v133
	v_ashrrev_i32_e32 v131, 31, v130
	v_add_u32_e32 v128, 0x8000, v128
	v_lshl_add_u64 v[140:141], v[136:137], 0, v[140:141]
	global_load_lds_dwordx4 v[138:139], off
	s_mov_b32 m0, s13
	v_lshlrev_b64 v[130:131], 13, v[130:131]
	v_readfirstlane_b32 s13, v128
	global_load_lds_dwordx4 v[140:141], off
	v_lshl_add_u64 v[130:131], v[134:135], 0, v[130:131]
	s_mov_b32 m0, s13
	v_add_u32_e32 v128, 0x8000, v142
	global_load_lds_dwordx4 v[130:131], off
	v_add_u32_e32 v130, v187, v148
	v_ashrrev_i32_e32 v131, 31, v130
	v_lshlrev_b64 v[130:131], 13, v[130:131]
	v_readfirstlane_b32 s13, v128
	v_lshl_add_u64 v[130:131], v[134:135], 0, v[130:131]
	s_mov_b32 m0, s13
	v_add_u32_e32 v128, 0x8000, v132
	global_load_lds_dwordx4 v[130:131], off
	v_add_u32_e32 v130, v186, v148
	v_ashrrev_i32_e32 v131, 31, v130
	v_lshlrev_b64 v[130:131], 13, v[130:131]
	v_readfirstlane_b32 s13, v128
	v_lshl_add_u64 v[130:131], v[134:135], 0, v[130:131]
	s_mov_b32 m0, s13
	v_add_u32_e32 v128, 0x8000, v133
	global_load_lds_dwordx4 v[130:131], off
	v_add_u32_e32 v130, v185, v148
	v_ashrrev_i32_e32 v131, 31, v130
	v_lshlrev_b64 v[130:131], 13, v[130:131]
	v_readfirstlane_b32 s13, v128
	v_lshl_add_u64 v[130:131], v[134:135], 0, v[130:131]
	s_mov_b32 m0, s13
	s_nop 0
	global_load_lds_dwordx4 v[130:131], off
